# attention: barrier+vmcnt moved mid-iteration (between QK and PV), LDS-DMA issue spread through PV gaps, no barrier at back-edge
# speedup vs baseline: 1.0039x; 1.0039x over previous
; #define AT_ADV() do { kg[0] += 64 * 1024; kg[1] += 64 * 1024; vg[0] += 64; vg[1] += 64; } while (0)
; __device__ __forceinline__ void attn_unit(unsigned char* ws, const float* sub_g, LAS unsigned char* lds, int h, int qb, float negM, float lam) {
;     ...
;     for (int t = 1; t < AT_NT; ++t) {
;         AT_DMA(bW);
;         if (t + 2 < AT_NT) AT_ADV();
;         SB();
;     ...
;         f32x16 s0, s1;
;         bf16x8 F0 = FLOAD(0), F1 = FLOAD(1), F2;
;         SB();
;         F2 = FLOAD(2); s0 = __builtin_amdgcn_mfma_f32_32x32x16_bf16(F0, qf[0], negm, 0, 0, 0); ADD4(pa, 0); pw[0][0] = cvtpk(pa[0], pa[1]); SB();
;         F0 = FLOAD(3); s1 = __builtin_amdgcn_mfma_f32_32x32x16_bf16(F1, qf[0], negm, 0, 0, 0); ADD4(pa, 4); pw[0][1] = cvtpk(pa[2], pa[3]); SB();
;         F1 = FLOAD(4); s0 = __builtin_amdgcn_mfma_f32_32x32x16_bf16(F2, qf[1], s0, 0, 0, 0); ADD4(pa, 8); pw[0][2] = cvtpk(pa[4], pa[5]); SB();
;         F2 = FLOAD(5); s1 = __builtin_amdgcn_mfma_f32_32x32x16_bf16(F0, qf[1], s1, 0, 0, 0); ADD4(pa, 12); pw[0][3] = cvtpk(pa[6], pa[7]); SB();
;         F0 = FLOAD(6); s0 = __builtin_amdgcn_mfma_f32_32x32x16_bf16(F1, qf[2], s0, 0, 0, 0); ADD4(pb, 0); pw[1][0] = cvtpk(pa[8], pa[9]); SB();
;         F1 = FLOAD(7); s1 = __builtin_amdgcn_mfma_f32_32x32x16_bf16(F2, qf[2], s1, 0, 0, 0); ADD4(pb, 4); pw[1][1] = cvtpk(pa[10], pa[11]); SB();
;         F2 = FLOAD(8); s0 = __builtin_amdgcn_mfma_f32_32x32x16_bf16(F0, qf[3], s0, 0, 0, 0); ADD4(pb, 8); pw[1][2] = cvtpk(pa[12], pa[13]); SB();
;         F0 = FLOAD(9); s1 = __builtin_amdgcn_mfma_f32_32x32x16_bf16(F1, qf[3], s1, 0, 0, 0); ADD4(pb, 12); pw[1][3] = cvtpk(pa[14], pa[15]); SB();
;         F1 = FLOAD(10); o[0] = __builtin_amdgcn_mfma_f32_32x32x16_bf16(F2, __builtin_bit_cast(bf16x8, pw[0]), o[0], 0, 0, 0); pw[2][0] = cvtpk(pb[0], pb[1]); EXP2(s0, pa, 0); SB();
;         F2 = FLOAD(11); o[1] = __builtin_amdgcn_mfma_f32_32x32x16_bf16(F0, __builtin_bit_cast(bf16x8, pw[0]), o[1], 0, 0, 0); pw[2][1] = cvtpk(pb[2], pb[3]); EXP2(s0, pa, 2); SB();
;         F0 = FLOAD(12); o[2] = __builtin_amdgcn_mfma_f32_32x32x16_bf16(F1, __builtin_bit_cast(bf16x8, pw[0]), o[2], 0, 0, 0); pw[2][2] = cvtpk(pb[4], pb[5]); EXP2(s0, pa, 4); SB();
;         F1 = FLOAD(13); o[3] = __builtin_amdgcn_mfma_f32_32x32x16_bf16(F2, __builtin_bit_cast(bf16x8, pw[0]), o[3], 0, 0, 0); pw[2][3] = cvtpk(pb[6], pb[7]); EXP2(s0, pa, 6); SB();
.LBB0_831:
	v_add_u32_e32 v84, s30, v198
	ds_read_b128 v[80:83], v84
	ds_read_b128 v[224:227], v84 offset:8192
	s_add_i32 s34, s30, 0
	v_add_u32_e32 v84, s34, v200
	ds_read_b128 v[228:231], v84
	v_add_f32_e32 v85, v216, v217
	v_add_f32_e32 v86, v199, v219
	s_waitcnt lgkmcnt(2)
	v_mfma_f32_32x32x16_bf16 v[96:111], v[80:83], v[112:115], v[0:15]
	v_add_f32_e32 v85, v85, v218
	v_add_f32_e32 v80, v86, v222
	v_cvt_pk_bf16_f32 v232, v217, v219
	ds_read_b128 v[236:239], v84 offset:8192
	v_add_f32_e32 v81, v85, v211
	v_add_f32_e32 v80, v80, v215
	v_cvt_pk_bf16_f32 v233, v218, v222
	v_add_f32_e32 v199, v81, v209
	v_add_f32_e32 v223, v80, v213
	s_waitcnt lgkmcnt(2)
	v_mfma_f32_32x32x16_bf16 v[80:95], v[224:227], v[112:115], v[0:15]
	v_add_u32_e32 v222, s34, v201
	ds_read_b128 v[216:219], v222
	v_add_f32_e32 v199, v199, v210
	v_add_f32_e32 v223, v223, v214
	s_waitcnt lgkmcnt(2)
	v_mfma_f32_32x32x16_bf16 v[96:111], v[228:231], v[116:119], v[96:111]
	v_add_f32_e32 v199, v199, v207
	v_add_f32_e32 v226, v223, v208
	v_cvt_pk_bf16_f32 v234, v211, v215
	ds_read_b128 v[222:225], v222 offset:8192
	v_add_f32_e32 v199, v199, v205
	v_add_f32_e32 v211, v226, v206
	v_cvt_pk_bf16_f32 v235, v209, v213
	v_add_f32_e32 v199, v199, v204
	v_add_f32_e32 v211, v211, v203
	s_waitcnt lgkmcnt(2)
	v_mfma_f32_32x32x16_bf16 v[80:95], v[236:239], v[116:119], v[80:95]
	v_add_u32_e32 v209, s34, v202
	ds_read_b128 v[226:229], v209
	v_add_f32_e32 v199, v199, v130
	v_add_f32_e32 v211, v211, v187
	s_waitcnt lgkmcnt(2)
	v_mfma_f32_32x32x16_bf16 v[96:111], v[216:219], v[120:123], v[96:111]
	v_add_f32_e32 v199, v199, v183
	v_add_f32_e32 v211, v211, v190
	v_cvt_pk_bf16_f32 v236, v210, v214
	ds_read_b128 v[240:243], v209 offset:8192
	v_add_f32_e32 v199, v199, v184
	v_add_f32_e32 v209, v211, v192
	v_cvt_pk_bf16_f32 v237, v207, v208
	v_add_f32_e32 v199, v199, v185
	v_add_f32_e32 v213, v209, v193
	s_waitcnt lgkmcnt(2)
	v_mfma_f32_32x32x16_bf16 v[80:95], v[222:225], v[120:123], v[80:95]
	s_add_i32 s36, s35, 0
	v_add_u32_e32 v214, s36, v178
	ds_read_b128 v[208:211], v214 offset:16384
	v_add_f32_e32 v199, v199, v188
	v_add_f32_e32 v207, v213, v196
	s_waitcnt lgkmcnt(2)
	v_mfma_f32_32x32x16_bf16 v[96:111], v[226:229], v[124:127], v[96:111]
	v_add_f32_e32 v199, v199, v191
	v_add_f32_e32 v207, v207, v197
	v_cvt_pk_bf16_f32 v238, v205, v206
	ds_read_b128 v[224:227], v214 offset:20480
	v_add_f32_e32 v199, v199, v189
	v_add_f32_e32 v205, v207, v194
	v_cvt_pk_bf16_f32 v239, v204, v203
	v_add_f32_e32 v216, v199, v186
	v_add_f32_e32 v199, v205, v195
	s_waitcnt lgkmcnt(2)
	v_mfma_f32_32x32x16_bf16 v[80:95], v[240:243], v[124:127], v[80:95]
	s_waitcnt vmcnt(0)
	s_barrier
	s_waitcnt lgkmcnt(1)
	v_mfma_f32_32x32x16_bf16 v[64:79], v[208:211], v[232:235], v[64:79]
	s_add_i32 m0, s8, s31
	ds_read_b128 v[204:207], v214 offset:24576
	global_load_lds_dwordx4 v[140:141], off
	s_nop 5
	v_exp_f32_e32 v217, v96
	v_exp_f32_e32 v219, v97
	v_cvt_pk_bf16_f32 v228, v130, v187
	s_waitcnt lgkmcnt(1)
	v_mfma_f32_32x32x16_bf16 v[48:63], v[224:227], v[232:235], v[48:63]
	ds_read_b128 v[240:243], v214 offset:28672
	v_exp_f32_e32 v218, v98
	v_exp_f32_e32 v222, v99
	v_cvt_pk_bf16_f32 v229, v183, v190
	s_waitcnt lgkmcnt(1)
	v_mfma_f32_32x32x16_bf16 v[32:47], v[204:207], v[232:235], v[32:47]
	s_add_i32 m0, m0, 0x4000
	v_add_u32_e32 v130, s36, v179
	ds_read_b128 v[96:99], v130 offset:16384
	global_load_lds_dwordx4 v[144:145], off
	v_exp_f32_e32 v211, v100
	v_exp_f32_e32 v215, v101
	v_cvt_pk_bf16_f32 v230, v184, v192
	s_waitcnt lgkmcnt(1)
	v_mfma_f32_32x32x16_bf16 v[16:31], v[240:243], v[232:235], v[16:31]
	ds_read_b128 v[224:227], v130 offset:20480
	v_exp_f32_e32 v209, v102
	v_exp_f32_e32 v213, v103
	v_cvt_pk_bf16_f32 v231, v185, v193
	s_waitcnt lgkmcnt(1)
	v_mfma_f32_32x32x16_bf16 v[64:79], v[96:99], v[236:239], v[64:79]
	s_add_i32 m0, m0, 0xffffc400
	ds_read_b128 v[100:103], v130 offset:24576
	global_load_lds_dwordx4 v[142:143], off
	v_exp_f32_e32 v210, v104
	v_exp_f32_e32 v214, v105
	v_cvt_pk_bf16_f32 v232, v188, v196
	s_waitcnt lgkmcnt(1)
	v_mfma_f32_32x32x16_bf16 v[48:63], v[224:227], v[236:239], v[48:63]
	ds_read_b128 v[96:99], v130 offset:28672
	v_exp_f32_e32 v207, v106
	v_exp_f32_e32 v208, v107
	v_cvt_pk_bf16_f32 v233, v191, v197
	s_waitcnt lgkmcnt(1)
	v_mfma_f32_32x32x16_bf16 v[32:47], v[100:103], v[236:239], v[32:47]
	s_add_i32 m0, m0, 0x4000
	v_add_u32_e32 v183, s36, v180
	ds_read_b128 v[104:107], v183 offset:16384
	global_load_lds_dwordx4 v[146:147], off
	s_cmpk_lt_u32 s33, 0x81
	s_cbranch_scc0 .Lattn_noadv
	v_lshl_add_u64 v[146:147], v[146:147], 0, s[12:13]
	v_lshl_add_u64 v[144:145], v[144:145], 0, s[12:13]
	v_lshl_add_u64 v[142:143], v[142:143], 0, s[10:11]
	v_lshl_add_u64 v[140:141], v[140:141], 0, s[10:11]
.Lattn_noadv:
	v_exp_f32_e32 v205, v108
	v_exp_f32_e32 v206, v109
	v_cvt_pk_bf16_f32 v234, v189, v194
	s_waitcnt lgkmcnt(1)
	v_mfma_f32_32x32x16_bf16 v[16:31], v[96:99], v[236:239], v[16:31]
	ds_read_b128 v[100:103], v183 offset:20480
	v_exp_f32_e32 v204, v110
	v_exp_f32_e32 v203, v111
	v_cvt_pk_bf16_f32 v235, v186, v195
	s_waitcnt lgkmcnt(1)
	v_mfma_f32_32x32x16_bf16 v[64:79], v[104:107], v[228:231], v[64:79]
	ds_read_b128 v[96:99], v183 offset:24576
	v_exp_f32_e32 v130, v80
	v_exp_f32_e32 v187, v81
	s_waitcnt lgkmcnt(1)
	v_mfma_f32_32x32x16_bf16 v[48:63], v[100:103], v[228:231], v[48:63]
	ds_read_b128 v[104:107], v183 offset:28672
	v_exp_f32_e32 v183, v82
	v_exp_f32_e32 v190, v83
	s_waitcnt lgkmcnt(1)
	v_mfma_f32_32x32x16_bf16 v[32:47], v[96:99], v[228:231], v[32:47]
	v_add_u32_e32 v100, s36, v181
	ds_read_b128 v[80:83], v100 offset:16384
	v_exp_f32_e32 v184, v84
	v_exp_f32_e32 v192, v85
	s_waitcnt lgkmcnt(1)
	v_mfma_f32_32x32x16_bf16 v[16:31], v[104:107], v[228:231], v[16:31]
	ds_read_b128 v[96:99], v100 offset:20480
	v_exp_f32_e32 v185, v86
	v_exp_f32_e32 v193, v87
	s_waitcnt lgkmcnt(1)
	v_mfma_f32_32x32x16_bf16 v[64:79], v[80:83], v[232:235], v[64:79]
	ds_read_b128 v[84:87], v100 offset:24576
	v_exp_f32_e32 v188, v88
	v_exp_f32_e32 v196, v89
	s_waitcnt lgkmcnt(1)
	v_mfma_f32_32x32x16_bf16 v[48:63], v[96:99], v[232:235], v[48:63]
	ds_read_b128 v[80:83], v100 offset:28672
	v_exp_f32_e32 v191, v90
	v_exp_f32_e32 v197, v91
	s_waitcnt lgkmcnt(1)
	v_mfma_f32_32x32x16_bf16 v[32:47], v[84:87], v[232:235], v[32:47]
	v_exp_f32_e32 v189, v92
	v_exp_f32_e32 v194, v93
	s_waitcnt lgkmcnt(0)
	v_mfma_f32_32x32x16_bf16 v[16:31], v[80:83], v[232:235], v[16:31]
	v_exp_f32_e32 v186, v94
	v_exp_f32_e32 v195, v95
	s_waitcnt lgkmcnt(0)
	s_mov_b32 s36, s30
	s_add_i32 s30, s30, 0x8000
	s_and_b32 s30, s30, 0x1ffff
	s_xor_b32 s31, s30, 0x10000
	s_add_i32 s33, s33, 1
	s_cmpk_eq_i32 s33, 0x84
	s_cbranch_scc1 .LBB0_834
.LBB0_832:
	s_mov_b32 s35, s36
	s_branch .LBB0_831
